# v36 plus GLU epilogue: all sixteen YG multiplicand reads requested at the top of the epilogue with counted waits instead of one exposed read per row group
# speedup vs baseline: 1.0003x; 1.0003x over previous
.LBB0_385:
	s_and_b64 s[4:5], s[6:7], exec
	s_cselect_b32 s0, 0x100, 0
	v_or_b32_e32 v58, s0, v78
	v_or_b32_e32 v60, s26, v58
	v_readlane_b32 s4, v242, 16
	v_lshlrev_b32_e32 v62, 2, v60
	v_readlane_b32 s12, v242, 24
	v_readlane_b32 s13, v242, 25
	s_nop 4
	global_load_dwordx4 v[74:77], v62, s[12:13] offset:16
	global_load_dwordx4 v[78:81], v62, s[12:13]
	v_add_u32_e32 v148, s99, v1
	v_ashrrev_i32_e32 v149, 31, v148
	v_lshlrev_b64 v[58:59], 10, v[148:149]
	v_lshl_add_u64 v[58:59], s[80:81], 0, v[58:59]
	v_lshlrev_b32_e32 v146, 1, v60
	v_mov_b32_e32 v147, 0
	v_lshl_add_u64 v[154:155], v[58:59], 0, v[146:147]
	global_load_dwordx4 v[150:153], v[154:155], off
	global_load_dwordx4 v[58:61], v62, s[12:13] offset:528
	s_nop 0
	global_load_dwordx4 v[62:65], v62, s[12:13] offset:512
	global_load_dwordx4 v[164:167], v[154:155], off offset:256
	s_mov_b32 s100, 0x4000
	s_mov_b32 s101, 0
	v_lshl_add_u64 v[228:229], s[100:101], 0, v[154:155]
	global_load_dwordx4 v[168:171], v[228:229], off
	global_load_dwordx4 v[172:175], v[228:229], off offset:256
	s_mov_b32 s100, 0x8000
	s_mov_b32 s101, 0
	v_lshl_add_u64 v[228:229], s[100:101], 0, v[154:155]
	global_load_dwordx4 v[176:179], v[228:229], off
	global_load_dwordx4 v[180:183], v[228:229], off offset:256
	s_mov_b32 s100, 0xfc568000
	s_mov_b32 s101, -1
	v_lshl_add_u64 v[228:229], s[100:101], 0, v[154:155]
	global_load_dwordx4 v[184:187], v[228:229], off
	global_load_dwordx4 v[188:191], v[228:229], off offset:256
	s_mov_b32 s100, 0x18000
	s_mov_b32 s101, 0
	v_lshl_add_u64 v[228:229], s[100:101], 0, v[154:155]
	global_load_dwordx4 v[192:195], v[228:229], off
	global_load_dwordx4 v[196:199], v[228:229], off offset:256
	s_mov_b32 s100, 0x1c000
	s_mov_b32 s101, 0
	v_lshl_add_u64 v[228:229], s[100:101], 0, v[154:155]
	global_load_dwordx4 v[200:203], v[228:229], off
	global_load_dwordx4 v[204:207], v[228:229], off offset:256
	s_mov_b32 s100, 0x20000
	s_mov_b32 s101, 0
	v_lshl_add_u64 v[228:229], s[100:101], 0, v[154:155]
	global_load_dwordx4 v[208:211], v[228:229], off
	global_load_dwordx4 v[216:219], v[228:229], off offset:256
	s_mov_b32 s100, 0xfc568000
	s_mov_b32 s101, -1
	v_lshl_add_u64 v[228:229], s[100:101], 0, v[154:155]
	global_load_dwordx4 v[220:223], v[228:229], off
	global_load_dwordx4 v[224:227], v[228:229], off offset:256
	v_readlane_b32 s5, v242, 17
	v_readlane_b32 s6, v242, 18
	v_readlane_b32 s7, v242, 19
	v_readlane_b32 s8, v242, 20
	v_readlane_b32 s9, v242, 21
	v_readlane_b32 s10, v242, 22
	v_readlane_b32 s11, v242, 23
	v_readlane_b32 s14, v242, 26
	v_readlane_b32 s15, v242, 27
	v_readlane_b32 s16, v242, 28
	v_readlane_b32 s17, v242, 29
	v_readlane_b32 s18, v242, 30
	v_readlane_b32 s19, v242, 31
	s_waitcnt vmcnt(15)
	v_add_f32_e32 v138, v138, v74
	v_add_f32_e32 v1, v142, v78
	v_add_f32_e32 v142, v143, v79
	v_add_f32_e32 v139, v139, v75
	v_add_f32_e32 v143, v144, v80
	v_add_f32_e32 v140, v140, v76
	v_add_f32_e32 v144, v145, v81
	v_add_f32_e32 v141, v141, v77
	v_mul_f32_e32 v1, 0xbfb8aa3b, v1
	v_mul_f32_e32 v138, 0xbfb8aa3b, v138
	v_mul_f32_e32 v142, 0xbfb8aa3b, v142
	v_mul_f32_e32 v139, 0xbfb8aa3b, v139
	v_mul_f32_e32 v143, 0xbfb8aa3b, v143
	v_mul_f32_e32 v140, 0xbfb8aa3b, v140
	v_mul_f32_e32 v144, 0xbfb8aa3b, v144
	v_mul_f32_e32 v141, 0xbfb8aa3b, v141
	v_exp_f32_e32 v1, v1
	v_exp_f32_e32 v138, v138
	v_exp_f32_e32 v142, v142
	v_exp_f32_e32 v139, v139
	v_exp_f32_e32 v143, v143
	v_exp_f32_e32 v140, v140
	v_exp_f32_e32 v144, v144
	v_exp_f32_e32 v141, v141
	v_add_f32_e32 v1, 1.0, v1
	v_add_f32_e32 v138, 1.0, v138
	v_add_f32_e32 v142, 1.0, v142
	v_add_f32_e32 v139, 1.0, v139
	v_add_f32_e32 v143, 1.0, v143
	v_add_f32_e32 v140, 1.0, v140
	v_add_f32_e32 v144, 1.0, v144
	v_add_f32_e32 v141, 1.0, v141
	v_rcp_f32_e32 v1, v1
	v_rcp_f32_e32 v138, v138
	v_rcp_f32_e32 v142, v142
	v_rcp_f32_e32 v139, v139
	v_rcp_f32_e32 v143, v143
	v_rcp_f32_e32 v140, v140
	v_rcp_f32_e32 v144, v144
	v_rcp_f32_e32 v141, v141
	v_lshlrev_b32_e32 v145, 16, v150
	v_and_b32_e32 v150, 0xffff0000, v150
	v_lshlrev_b32_e32 v156, 16, v151
	v_and_b32_e32 v151, 0xffff0000, v151
	v_lshlrev_b32_e32 v157, 16, v152
	v_and_b32_e32 v152, 0xffff0000, v152
	v_lshlrev_b32_e32 v158, 16, v153
	v_and_b32_e32 v153, 0xffff0000, v153
	v_mul_f32_e32 v1, v1, v145
	v_mul_f32_e32 v145, v138, v157
	v_mul_f32_e32 v138, v142, v150
	v_mul_f32_e32 v142, v139, v152
	v_mul_f32_e32 v139, v143, v156
	v_mul_f32_e32 v143, v140, v158
	v_mul_f32_e32 v140, v144, v151
	v_mul_f32_e32 v141, v141, v153
	v_cvt_pk_bf16_f32 v138, v1, v138
	v_cvt_pk_bf16_f32 v139, v139, v140
	v_cvt_pk_bf16_f32 v140, v145, v142
	v_cvt_pk_bf16_f32 v141, v143, v141
	v_add_f32_e32 v1, v134, v62
	v_add_f32_e32 v130, v130, v58
	v_add_f32_e32 v134, v135, v63
	v_add_f32_e32 v131, v131, v59
	v_add_f32_e32 v135, v136, v64
	v_add_f32_e32 v132, v132, v60
	v_add_f32_e32 v136, v137, v65
	v_add_f32_e32 v133, v133, v61
	v_mul_f32_e32 v1, 0xbfb8aa3b, v1
	v_mul_f32_e32 v130, 0xbfb8aa3b, v130
	v_mul_f32_e32 v134, 0xbfb8aa3b, v134
	v_mul_f32_e32 v131, 0xbfb8aa3b, v131
	v_mul_f32_e32 v135, 0xbfb8aa3b, v135
	v_mul_f32_e32 v132, 0xbfb8aa3b, v132
	v_mul_f32_e32 v136, 0xbfb8aa3b, v136
	v_mul_f32_e32 v133, 0xbfb8aa3b, v133
	v_exp_f32_e32 v1, v1
	v_exp_f32_e32 v130, v130
	v_exp_f32_e32 v134, v134
	v_exp_f32_e32 v131, v131
	v_exp_f32_e32 v135, v135
	v_exp_f32_e32 v132, v132
	v_exp_f32_e32 v136, v136
	v_exp_f32_e32 v133, v133
	v_add_f32_e32 v1, 1.0, v1
	v_add_f32_e32 v130, 1.0, v130
	v_add_f32_e32 v134, 1.0, v134
	v_add_f32_e32 v131, 1.0, v131
	v_add_f32_e32 v135, 1.0, v135
	v_add_f32_e32 v132, 1.0, v132
	v_add_f32_e32 v136, 1.0, v136
	v_add_f32_e32 v133, 1.0, v133
	v_add_u32_e32 v150, 16, v148
	v_lshlrev_b64 v[152:153], 11, v[148:149]
	v_rcp_f32_e32 v1, v1
	v_rcp_f32_e32 v130, v130
	v_rcp_f32_e32 v134, v134
	v_rcp_f32_e32 v131, v131
	v_rcp_f32_e32 v135, v135
	v_rcp_f32_e32 v132, v132
	v_rcp_f32_e32 v136, v136
	v_rcp_f32_e32 v133, v133
	v_ashrrev_i32_e32 v151, 31, v150
	v_lshl_add_u64 v[152:153], s[60:61], 0, v[152:153]
	v_lshlrev_b64 v[154:155], 10, v[150:151]
	v_lshl_add_u64 v[152:153], v[152:153], 0, v[146:147]
	v_lshl_add_u64 v[154:155], s[80:81], 0, v[154:155]
	global_store_dwordx4 v[152:153], v[138:141], off offset:1024
	v_lshl_add_u64 v[154:155], v[154:155], 0, v[146:147]
	v_add_f32_e32 v122, v122, v74
	v_add_f32_e32 v123, v123, v75
	v_add_f32_e32 v124, v124, v76
	v_add_f32_e32 v125, v125, v77
	v_mul_f32_e32 v122, 0xbfb8aa3b, v122
	v_mul_f32_e32 v123, 0xbfb8aa3b, v123
	v_mul_f32_e32 v124, 0xbfb8aa3b, v124
	v_mul_f32_e32 v125, 0xbfb8aa3b, v125
	v_exp_f32_e32 v122, v122
	v_exp_f32_e32 v123, v123
	v_exp_f32_e32 v124, v124
	v_exp_f32_e32 v125, v125
	v_add_f32_e32 v122, 1.0, v122
	v_add_f32_e32 v123, 1.0, v123
	v_add_f32_e32 v124, 1.0, v124
	v_add_f32_e32 v125, 1.0, v125
	v_rcp_f32_e32 v122, v122
	v_rcp_f32_e32 v123, v123
	v_rcp_f32_e32 v124, v124
	v_rcp_f32_e32 v125, v125
	v_add_f32_e32 v114, v114, v58
	v_add_f32_e32 v115, v115, v59
	v_add_f32_e32 v116, v116, v60
	v_add_f32_e32 v117, v117, v61
	v_mul_f32_e32 v114, 0xbfb8aa3b, v114
	v_mul_f32_e32 v115, 0xbfb8aa3b, v115
	v_mul_f32_e32 v116, 0xbfb8aa3b, v116
	v_mul_f32_e32 v117, 0xbfb8aa3b, v117
	v_exp_f32_e32 v114, v114
	v_exp_f32_e32 v115, v115
	s_waitcnt vmcnt(15)
	v_mov_b32_e32 v142, v164
	v_mov_b32_e32 v143, v165
	v_mov_b32_e32 v144, v166
	v_mov_b32_e32 v145, v167
	v_lshlrev_b32_e32 v137, 16, v142
	v_and_b32_e32 v138, 0xffff0000, v142
	v_lshlrev_b32_e32 v139, 16, v143
	v_and_b32_e32 v140, 0xffff0000, v143
	v_lshlrev_b32_e32 v141, 16, v144
	v_and_b32_e32 v142, 0xffff0000, v144
	v_lshlrev_b32_e32 v143, 16, v145
	v_and_b32_e32 v144, 0xffff0000, v145
	v_mul_f32_e32 v1, v1, v137
	v_mul_f32_e32 v137, v130, v141
	v_mul_f32_e32 v130, v134, v138
	v_mul_f32_e32 v134, v131, v142
	v_mul_f32_e32 v131, v135, v139
	v_mul_f32_e32 v135, v132, v143
	v_mul_f32_e32 v132, v136, v140
	v_mul_f32_e32 v133, v133, v144
	v_cvt_pk_bf16_f32 v130, v1, v130
	v_cvt_pk_bf16_f32 v131, v131, v132
	v_cvt_pk_bf16_f32 v132, v137, v134
	v_cvt_pk_bf16_f32 v133, v135, v133
	v_add_f32_e32 v1, v126, v78
	v_add_f32_e32 v126, v127, v79
	v_add_f32_e32 v127, v128, v80
	v_add_f32_e32 v128, v129, v81
	v_mul_f32_e32 v1, 0xbfb8aa3b, v1
	v_mul_f32_e32 v126, 0xbfb8aa3b, v126
	v_mul_f32_e32 v127, 0xbfb8aa3b, v127
	v_mul_f32_e32 v128, 0xbfb8aa3b, v128
	v_exp_f32_e32 v1, v1
	v_exp_f32_e32 v126, v126
	v_exp_f32_e32 v127, v127
	v_exp_f32_e32 v128, v128
	v_add_f32_e32 v1, 1.0, v1
	v_add_f32_e32 v126, 1.0, v126
	v_add_f32_e32 v127, 1.0, v127
	v_add_f32_e32 v128, 1.0, v128
	v_rcp_f32_e32 v1, v1
	v_rcp_f32_e32 v126, v126
	v_rcp_f32_e32 v127, v127
	v_rcp_f32_e32 v128, v128
	global_store_dwordx4 v[152:153], v[130:133], off offset:1280
	v_exp_f32_e32 v116, v116
	v_exp_f32_e32 v117, v117
	v_add_f32_e32 v114, 1.0, v114
	v_add_f32_e32 v115, 1.0, v115
	v_add_f32_e32 v116, 1.0, v116
	v_add_f32_e32 v117, 1.0, v117
	v_rcp_f32_e32 v114, v114
	v_rcp_f32_e32 v115, v115
	v_rcp_f32_e32 v116, v116
	v_rcp_f32_e32 v117, v117
	v_add_f32_e32 v106, v106, v74
	v_add_f32_e32 v107, v107, v75
	v_add_f32_e32 v108, v108, v76
	v_add_f32_e32 v109, v109, v77
	v_mul_f32_e32 v106, 0xbfb8aa3b, v106
	v_mul_f32_e32 v107, 0xbfb8aa3b, v107
	v_mul_f32_e32 v108, 0xbfb8aa3b, v108
	v_mul_f32_e32 v109, 0xbfb8aa3b, v109
	v_exp_f32_e32 v106, v106
	v_exp_f32_e32 v107, v107
	v_exp_f32_e32 v108, v108
	v_exp_f32_e32 v109, v109
	v_add_f32_e32 v106, 1.0, v106
	v_add_f32_e32 v107, 1.0, v107
	v_add_f32_e32 v108, 1.0, v108
	v_add_f32_e32 v109, 1.0, v109
	v_rcp_f32_e32 v106, v106
	v_rcp_f32_e32 v107, v107
	v_rcp_f32_e32 v108, v108
	v_rcp_f32_e32 v109, v109
	v_add_f32_e32 v98, v98, v58
	v_add_f32_e32 v99, v99, v59
	v_add_f32_e32 v100, v100, v60
	v_add_f32_e32 v101, v101, v61
	v_mul_f32_e32 v98, 0xbfb8aa3b, v98
	v_mul_f32_e32 v99, 0xbfb8aa3b, v99
	v_mul_f32_e32 v100, 0xbfb8aa3b, v100
	v_mul_f32_e32 v101, 0xbfb8aa3b, v101
	v_exp_f32_e32 v98, v98
	v_exp_f32_e32 v99, v99
	v_exp_f32_e32 v100, v100
	v_exp_f32_e32 v101, v101
	v_add_f32_e32 v98, 1.0, v98
	v_add_f32_e32 v99, 1.0, v99
	v_add_f32_e32 v100, 1.0, v100
	v_add_f32_e32 v101, 1.0, v101
	v_rcp_f32_e32 v98, v98
	v_rcp_f32_e32 v99, v99
	v_rcp_f32_e32 v100, v100
	v_rcp_f32_e32 v101, v101
	v_add_f32_e32 v90, v90, v74
	v_add_f32_e32 v91, v91, v75
	v_add_f32_e32 v92, v92, v76
	v_add_f32_e32 v93, v93, v77
	v_mul_f32_e32 v90, 0xbfb8aa3b, v90
	v_mul_f32_e32 v91, 0xbfb8aa3b, v91
	v_mul_f32_e32 v92, 0xbfb8aa3b, v92
	v_mul_f32_e32 v93, 0xbfb8aa3b, v93
	s_waitcnt vmcnt(15)
	v_mov_b32_e32 v134, v168
	v_mov_b32_e32 v135, v169
	v_mov_b32_e32 v136, v170
	v_mov_b32_e32 v137, v171
	v_lshlrev_b32_e32 v129, 16, v134
	v_and_b32_e32 v130, 0xffff0000, v134
	v_lshlrev_b32_e32 v131, 16, v135
	v_and_b32_e32 v132, 0xffff0000, v135
	v_lshlrev_b32_e32 v133, 16, v136
	v_and_b32_e32 v134, 0xffff0000, v136
	v_lshlrev_b32_e32 v135, 16, v137
	v_and_b32_e32 v136, 0xffff0000, v137
	v_mul_f32_e32 v1, v1, v129
	v_mul_f32_e32 v129, v122, v133
	v_mul_f32_e32 v122, v126, v130
	v_mul_f32_e32 v126, v123, v134
	v_mul_f32_e32 v123, v127, v131
	v_mul_f32_e32 v127, v124, v135
	v_mul_f32_e32 v124, v128, v132
	v_mul_f32_e32 v125, v125, v136
	v_cvt_pk_bf16_f32 v122, v1, v122
	v_cvt_pk_bf16_f32 v123, v123, v124
	v_cvt_pk_bf16_f32 v124, v129, v126
	v_cvt_pk_bf16_f32 v125, v127, v125
	v_add_f32_e32 v1, v118, v62
	v_add_f32_e32 v118, v119, v63
	v_add_f32_e32 v119, v120, v64
	v_add_f32_e32 v120, v121, v65
	v_mul_f32_e32 v1, 0xbfb8aa3b, v1
	v_mul_f32_e32 v118, 0xbfb8aa3b, v118
	v_mul_f32_e32 v119, 0xbfb8aa3b, v119
	v_mul_f32_e32 v120, 0xbfb8aa3b, v120
	v_exp_f32_e32 v1, v1
	v_exp_f32_e32 v118, v118
	v_exp_f32_e32 v119, v119
	v_exp_f32_e32 v120, v120
	v_add_f32_e32 v1, 1.0, v1
	v_add_f32_e32 v118, 1.0, v118
	v_add_f32_e32 v119, 1.0, v119
	v_add_f32_e32 v120, 1.0, v120
	v_add_u32_e32 v130, 32, v148
	v_lshlrev_b64 v[132:133], 11, v[150:151]
	v_rcp_f32_e32 v1, v1
	v_rcp_f32_e32 v118, v118
	v_rcp_f32_e32 v119, v119
	v_rcp_f32_e32 v120, v120
	v_ashrrev_i32_e32 v131, 31, v130
	v_lshl_add_u64 v[132:133], s[60:61], 0, v[132:133]
	v_lshlrev_b64 v[134:135], 10, v[130:131]
	v_lshl_add_u64 v[132:133], v[132:133], 0, v[146:147]
	v_lshl_add_u64 v[134:135], s[80:81], 0, v[134:135]
	global_store_dwordx4 v[132:133], v[122:125], off offset:1024
	v_lshl_add_u64 v[134:135], v[134:135], 0, v[146:147]
	v_exp_f32_e32 v90, v90
	v_exp_f32_e32 v91, v91
	v_exp_f32_e32 v92, v92
	v_exp_f32_e32 v93, v93
	v_add_f32_e32 v90, 1.0, v90
	v_add_f32_e32 v91, 1.0, v91
	v_add_f32_e32 v92, 1.0, v92
	v_add_f32_e32 v93, 1.0, v93
	v_rcp_f32_e32 v90, v90
	v_rcp_f32_e32 v91, v91
	v_rcp_f32_e32 v92, v92
	v_rcp_f32_e32 v93, v93
	v_add_f32_e32 v82, v82, v58
	v_add_f32_e32 v83, v83, v59
	v_add_f32_e32 v84, v84, v60
	v_add_f32_e32 v85, v85, v61
	v_mul_f32_e32 v82, 0xbfb8aa3b, v82
	v_mul_f32_e32 v83, 0xbfb8aa3b, v83
	v_mul_f32_e32 v84, 0xbfb8aa3b, v84
	v_mul_f32_e32 v85, 0xbfb8aa3b, v85
	v_exp_f32_e32 v82, v82
	v_exp_f32_e32 v83, v83
	v_exp_f32_e32 v84, v84
	v_exp_f32_e32 v85, v85
	v_add_f32_e32 v82, 1.0, v82
	v_add_f32_e32 v83, 1.0, v83
	v_add_f32_e32 v84, 1.0, v84
	v_add_f32_e32 v85, 1.0, v85
	v_rcp_f32_e32 v82, v82
	v_rcp_f32_e32 v83, v83
	v_rcp_f32_e32 v84, v84
	v_rcp_f32_e32 v85, v85
	v_add_f32_e32 v66, v66, v74
	v_add_f32_e32 v67, v67, v75
	v_add_f32_e32 v68, v68, v76
	v_add_f32_e32 v69, v69, v77
	v_mul_f32_e32 v66, 0xbfb8aa3b, v66
	v_mul_f32_e32 v67, 0xbfb8aa3b, v67
	v_mul_f32_e32 v68, 0xbfb8aa3b, v68
	v_mul_f32_e32 v69, 0xbfb8aa3b, v69
	v_exp_f32_e32 v66, v66
	v_exp_f32_e32 v67, v67
	v_exp_f32_e32 v68, v68
	v_exp_f32_e32 v69, v69
	v_add_f32_e32 v66, 1.0, v66
	v_add_f32_e32 v67, 1.0, v67
	v_add_f32_e32 v68, 1.0, v68
	v_add_f32_e32 v69, 1.0, v69
	v_rcp_f32_e32 v66, v66
	v_rcp_f32_e32 v67, v67
	s_waitcnt vmcnt(15)
	v_mov_b32_e32 v126, v172
	v_mov_b32_e32 v127, v173
	v_mov_b32_e32 v128, v174
	v_mov_b32_e32 v129, v175
	v_lshlrev_b32_e32 v121, 16, v126
	v_and_b32_e32 v122, 0xffff0000, v126
	v_lshlrev_b32_e32 v123, 16, v127
	v_and_b32_e32 v124, 0xffff0000, v127
	v_lshlrev_b32_e32 v125, 16, v128
	v_and_b32_e32 v126, 0xffff0000, v128
	v_lshlrev_b32_e32 v127, 16, v129
	v_and_b32_e32 v128, 0xffff0000, v129
	v_mul_f32_e32 v1, v1, v121
	v_mul_f32_e32 v121, v114, v125
	v_mul_f32_e32 v114, v118, v122
	v_mul_f32_e32 v118, v115, v126
	v_mul_f32_e32 v115, v119, v123
	v_mul_f32_e32 v119, v116, v127
	v_mul_f32_e32 v116, v120, v124
	v_mul_f32_e32 v117, v117, v128
	v_cvt_pk_bf16_f32 v114, v1, v114
	v_cvt_pk_bf16_f32 v115, v115, v116
	v_cvt_pk_bf16_f32 v116, v121, v118
	v_cvt_pk_bf16_f32 v117, v119, v117
	v_add_f32_e32 v1, v110, v78
	v_add_f32_e32 v110, v111, v79
	v_add_f32_e32 v111, v112, v80
	v_add_f32_e32 v112, v113, v81
	v_mul_f32_e32 v1, 0xbfb8aa3b, v1
	v_mul_f32_e32 v110, 0xbfb8aa3b, v110
	v_mul_f32_e32 v111, 0xbfb8aa3b, v111
	v_mul_f32_e32 v112, 0xbfb8aa3b, v112
	v_exp_f32_e32 v1, v1
	v_exp_f32_e32 v110, v110
	v_exp_f32_e32 v111, v111
	v_exp_f32_e32 v112, v112
	v_add_f32_e32 v1, 1.0, v1
	v_add_f32_e32 v110, 1.0, v110
	v_add_f32_e32 v111, 1.0, v111
	v_add_f32_e32 v112, 1.0, v112
	v_rcp_f32_e32 v1, v1
	v_rcp_f32_e32 v110, v110
	v_rcp_f32_e32 v111, v111
	v_rcp_f32_e32 v112, v112
	global_store_dwordx4 v[132:133], v[114:117], off offset:1280
	v_rcp_f32_e32 v68, v68
	v_rcp_f32_e32 v69, v69
	v_add_f32_e32 v50, v50, v58
	v_add_f32_e32 v51, v51, v59
	v_add_f32_e32 v52, v52, v60
	v_add_f32_e32 v53, v53, v61
	v_mul_f32_e32 v50, 0xbfb8aa3b, v50
	v_mul_f32_e32 v51, 0xbfb8aa3b, v51
	v_mul_f32_e32 v52, 0xbfb8aa3b, v52
	v_mul_f32_e32 v53, 0xbfb8aa3b, v53
	v_exp_f32_e32 v50, v50
	v_exp_f32_e32 v51, v51
	v_exp_f32_e32 v52, v52
	v_exp_f32_e32 v53, v53
	v_add_f32_e32 v50, 1.0, v50
	v_add_f32_e32 v51, 1.0, v51
	v_add_f32_e32 v52, 1.0, v52
	v_add_f32_e32 v53, 1.0, v53
	v_rcp_f32_e32 v50, v50
	v_rcp_f32_e32 v51, v51
	v_rcp_f32_e32 v52, v52
	v_rcp_f32_e32 v53, v53
	v_add_f32_e32 v42, v42, v74
	v_add_f32_e32 v43, v43, v75
	v_add_f32_e32 v44, v44, v76
	v_add_f32_e32 v45, v45, v77
	v_mul_f32_e32 v42, 0xbfb8aa3b, v42
	v_mul_f32_e32 v43, 0xbfb8aa3b, v43
	v_mul_f32_e32 v44, 0xbfb8aa3b, v44
	v_mul_f32_e32 v45, 0xbfb8aa3b, v45
	v_exp_f32_e32 v42, v42
	v_exp_f32_e32 v43, v43
	v_exp_f32_e32 v44, v44
	v_exp_f32_e32 v45, v45
	v_add_f32_e32 v42, 1.0, v42
	v_add_f32_e32 v43, 1.0, v43
	v_add_f32_e32 v44, 1.0, v44
	v_add_f32_e32 v45, 1.0, v45
	v_rcp_f32_e32 v42, v42
	v_rcp_f32_e32 v43, v43
	v_rcp_f32_e32 v44, v44
	v_rcp_f32_e32 v45, v45
	v_add_f32_e32 v34, v34, v58
	v_add_f32_e32 v35, v35, v59
	v_add_f32_e32 v36, v36, v60
	v_add_f32_e32 v37, v37, v61
	v_mul_f32_e32 v34, 0xbfb8aa3b, v34
	v_mul_f32_e32 v35, 0xbfb8aa3b, v35
	v_mul_f32_e32 v36, 0xbfb8aa3b, v36
	v_mul_f32_e32 v37, 0xbfb8aa3b, v37
	v_exp_f32_e32 v34, v34
	v_exp_f32_e32 v35, v35
	v_exp_f32_e32 v36, v36
	v_exp_f32_e32 v37, v37
	v_add_f32_e32 v34, 1.0, v34
	v_add_f32_e32 v35, 1.0, v35
	v_add_f32_e32 v36, 1.0, v36
	v_add_f32_e32 v37, 1.0, v37
	s_waitcnt vmcnt(15)
	v_mov_b32_e32 v118, v176
	v_mov_b32_e32 v119, v177
	v_mov_b32_e32 v120, v178
	v_mov_b32_e32 v121, v179
	v_lshlrev_b32_e32 v113, 16, v118
	v_and_b32_e32 v114, 0xffff0000, v118
	v_lshlrev_b32_e32 v115, 16, v119
	v_and_b32_e32 v116, 0xffff0000, v119
	v_lshlrev_b32_e32 v117, 16, v120
	v_and_b32_e32 v118, 0xffff0000, v120
	v_lshlrev_b32_e32 v119, 16, v121
	v_and_b32_e32 v120, 0xffff0000, v121
	v_mul_f32_e32 v1, v1, v113
	v_mul_f32_e32 v113, v106, v117
	v_mul_f32_e32 v106, v110, v114
	v_mul_f32_e32 v110, v107, v118
	v_mul_f32_e32 v107, v111, v115
	v_mul_f32_e32 v111, v108, v119
	v_mul_f32_e32 v108, v112, v116
	v_mul_f32_e32 v109, v109, v120
	v_cvt_pk_bf16_f32 v106, v1, v106
	v_cvt_pk_bf16_f32 v107, v107, v108
	v_cvt_pk_bf16_f32 v108, v113, v110
	v_cvt_pk_bf16_f32 v109, v111, v109
	v_add_f32_e32 v1, v102, v62
	v_add_f32_e32 v102, v103, v63
	v_add_f32_e32 v103, v104, v64
	v_add_f32_e32 v104, v105, v65
	v_mul_f32_e32 v1, 0xbfb8aa3b, v1
	v_mul_f32_e32 v102, 0xbfb8aa3b, v102
	v_mul_f32_e32 v103, 0xbfb8aa3b, v103
	v_mul_f32_e32 v104, 0xbfb8aa3b, v104
	v_exp_f32_e32 v1, v1
	v_exp_f32_e32 v102, v102
	v_exp_f32_e32 v103, v103
	v_exp_f32_e32 v104, v104
	v_add_f32_e32 v1, 1.0, v1
	v_add_f32_e32 v102, 1.0, v102
	v_add_f32_e32 v103, 1.0, v103
	v_add_f32_e32 v104, 1.0, v104
	v_add_u32_e32 v114, 0xffff15a0, v148
	v_lshlrev_b64 v[116:117], 11, v[130:131]
	v_rcp_f32_e32 v1, v1
	v_rcp_f32_e32 v102, v102
	v_rcp_f32_e32 v103, v103
	v_rcp_f32_e32 v104, v104
	v_ashrrev_i32_e32 v115, 31, v114
	v_lshl_add_u64 v[116:117], s[60:61], 0, v[116:117]
	v_lshlrev_b64 v[118:119], 10, v[114:115]
	v_lshl_add_u64 v[116:117], v[116:117], 0, v[146:147]
	v_lshl_add_u64 v[118:119], s[80:81], 0, v[118:119]
	global_store_dwordx4 v[116:117], v[106:109], off offset:1024
	v_lshl_add_u64 v[118:119], v[118:119], 0, v[146:147]
	v_rcp_f32_e32 v34, v34
	v_rcp_f32_e32 v35, v35
	v_rcp_f32_e32 v36, v36
	v_rcp_f32_e32 v37, v37
	v_add_f32_e32 v26, v26, v74
	v_add_f32_e32 v27, v27, v75
	v_add_f32_e32 v28, v28, v76
	v_add_f32_e32 v29, v29, v77
	v_mul_f32_e32 v26, 0xbfb8aa3b, v26
	v_mul_f32_e32 v27, 0xbfb8aa3b, v27
	v_mul_f32_e32 v28, 0xbfb8aa3b, v28
	v_mul_f32_e32 v29, 0xbfb8aa3b, v29
	v_exp_f32_e32 v26, v26
	v_exp_f32_e32 v27, v27
	v_exp_f32_e32 v28, v28
	v_exp_f32_e32 v29, v29
	v_add_f32_e32 v26, 1.0, v26
	v_add_f32_e32 v27, 1.0, v27
	v_add_f32_e32 v28, 1.0, v28
	v_add_f32_e32 v29, 1.0, v29
	v_rcp_f32_e32 v26, v26
	v_rcp_f32_e32 v27, v27
	v_rcp_f32_e32 v28, v28
	v_rcp_f32_e32 v29, v29
	v_add_f32_e32 v18, v18, v58
	v_add_f32_e32 v19, v19, v59
	v_add_f32_e32 v20, v20, v60
	v_add_f32_e32 v21, v21, v61
	v_mul_f32_e32 v18, 0xbfb8aa3b, v18
	v_mul_f32_e32 v19, 0xbfb8aa3b, v19
	v_mul_f32_e32 v20, 0xbfb8aa3b, v20
	v_mul_f32_e32 v21, 0xbfb8aa3b, v21
	v_exp_f32_e32 v18, v18
	v_exp_f32_e32 v19, v19
	v_exp_f32_e32 v20, v20
	v_exp_f32_e32 v21, v21
	v_add_f32_e32 v18, 1.0, v18
	v_add_f32_e32 v19, 1.0, v19
	v_add_f32_e32 v20, 1.0, v20
	v_add_f32_e32 v21, 1.0, v21
	v_rcp_f32_e32 v18, v18
	v_rcp_f32_e32 v19, v19
	v_rcp_f32_e32 v20, v20
	v_rcp_f32_e32 v21, v21
	v_add_f32_e32 v10, v10, v74
	v_add_f32_e32 v11, v11, v75
	v_add_f32_e32 v12, v12, v76
	v_add_f32_e32 v13, v13, v77
	v_mul_f32_e32 v10, 0xbfb8aa3b, v10
	v_mul_f32_e32 v11, 0xbfb8aa3b, v11
	s_waitcnt vmcnt(15)
	v_mov_b32_e32 v110, v180
	v_mov_b32_e32 v111, v181
	v_mov_b32_e32 v112, v182
	v_mov_b32_e32 v113, v183
	v_lshlrev_b32_e32 v105, 16, v110
	v_and_b32_e32 v106, 0xffff0000, v110
	v_lshlrev_b32_e32 v107, 16, v111
	v_and_b32_e32 v108, 0xffff0000, v111
	v_lshlrev_b32_e32 v109, 16, v112
	v_and_b32_e32 v110, 0xffff0000, v112
	v_lshlrev_b32_e32 v111, 16, v113
	v_and_b32_e32 v112, 0xffff0000, v113
	v_mul_f32_e32 v1, v1, v105
	v_mul_f32_e32 v105, v98, v109
	v_mul_f32_e32 v98, v102, v106
	v_mul_f32_e32 v102, v99, v110
	v_mul_f32_e32 v99, v103, v107
	v_mul_f32_e32 v103, v100, v111
	v_mul_f32_e32 v100, v104, v108
	v_mul_f32_e32 v101, v101, v112
	v_cvt_pk_bf16_f32 v98, v1, v98
	v_cvt_pk_bf16_f32 v99, v99, v100
	v_cvt_pk_bf16_f32 v100, v105, v102
	v_cvt_pk_bf16_f32 v101, v103, v101
	v_add_f32_e32 v1, v94, v78
	v_add_f32_e32 v94, v95, v79
	v_add_f32_e32 v95, v96, v80
	v_add_f32_e32 v96, v97, v81
	v_mul_f32_e32 v1, 0xbfb8aa3b, v1
	v_mul_f32_e32 v94, 0xbfb8aa3b, v94
	v_mul_f32_e32 v95, 0xbfb8aa3b, v95
	v_mul_f32_e32 v96, 0xbfb8aa3b, v96
	v_exp_f32_e32 v1, v1
	v_exp_f32_e32 v94, v94
	v_exp_f32_e32 v95, v95
	v_exp_f32_e32 v96, v96
	v_add_f32_e32 v1, 1.0, v1
	v_add_f32_e32 v94, 1.0, v94
	v_add_f32_e32 v95, 1.0, v95
	v_add_f32_e32 v96, 1.0, v96
	v_rcp_f32_e32 v1, v1
	v_rcp_f32_e32 v94, v94
	v_rcp_f32_e32 v95, v95
	v_rcp_f32_e32 v96, v96
	global_store_dwordx4 v[116:117], v[98:101], off offset:1280
	v_mul_f32_e32 v12, 0xbfb8aa3b, v12
	v_mul_f32_e32 v13, 0xbfb8aa3b, v13
	v_exp_f32_e32 v10, v10
	v_exp_f32_e32 v11, v11
	v_exp_f32_e32 v12, v12
	v_exp_f32_e32 v13, v13
	v_add_f32_e32 v10, 1.0, v10
	v_add_f32_e32 v11, 1.0, v11
	v_add_f32_e32 v12, 1.0, v12
	v_add_f32_e32 v13, 1.0, v13
	v_rcp_f32_e32 v10, v10
	v_rcp_f32_e32 v11, v11
	v_rcp_f32_e32 v12, v12
	v_rcp_f32_e32 v13, v13
	v_add_f32_e32 v2, v2, v58
	v_add_f32_e32 v3, v3, v59
	v_add_f32_e32 v4, v4, v60
	v_add_f32_e32 v5, v5, v61
	v_mul_f32_e32 v2, 0xbfb8aa3b, v2
	v_mul_f32_e32 v3, 0xbfb8aa3b, v3
	v_mul_f32_e32 v4, 0xbfb8aa3b, v4
	v_mul_f32_e32 v5, 0xbfb8aa3b, v5
	v_exp_f32_e32 v2, v2
	v_exp_f32_e32 v3, v3
	v_exp_f32_e32 v4, v4
	v_exp_f32_e32 v5, v5
	v_add_f32_e32 v2, 1.0, v2
	v_add_f32_e32 v3, 1.0, v3
	v_add_f32_e32 v4, 1.0, v4
	v_add_f32_e32 v5, 1.0, v5
	v_rcp_f32_e32 v2, v2
	v_rcp_f32_e32 v3, v3
	v_rcp_f32_e32 v4, v4
	v_rcp_f32_e32 v5, v5
	s_waitcnt vmcnt(15)
	v_mov_b32_e32 v102, v184
	v_mov_b32_e32 v103, v185
	v_mov_b32_e32 v104, v186
	v_mov_b32_e32 v105, v187
	v_lshlrev_b32_e32 v97, 16, v102
	v_and_b32_e32 v98, 0xffff0000, v102
	v_lshlrev_b32_e32 v99, 16, v103
	v_and_b32_e32 v100, 0xffff0000, v103
	v_lshlrev_b32_e32 v101, 16, v104
	v_and_b32_e32 v102, 0xffff0000, v104
	v_lshlrev_b32_e32 v103, 16, v105
	v_and_b32_e32 v104, 0xffff0000, v105
	v_mul_f32_e32 v1, v1, v97
	v_mul_f32_e32 v97, v90, v101
	v_mul_f32_e32 v90, v94, v98
	v_mul_f32_e32 v94, v91, v102
	v_mul_f32_e32 v91, v95, v99
	v_mul_f32_e32 v95, v92, v103
	v_mul_f32_e32 v92, v96, v100
	v_mul_f32_e32 v93, v93, v104
	v_cvt_pk_bf16_f32 v90, v1, v90
	v_cvt_pk_bf16_f32 v91, v91, v92
	v_cvt_pk_bf16_f32 v92, v97, v94
	v_cvt_pk_bf16_f32 v93, v95, v93
	v_add_f32_e32 v1, v86, v62
	v_add_f32_e32 v86, v87, v63
	v_add_f32_e32 v87, v88, v64
	v_add_f32_e32 v88, v89, v65
	v_mul_f32_e32 v1, 0xbfb8aa3b, v1
	v_mul_f32_e32 v86, 0xbfb8aa3b, v86
	v_mul_f32_e32 v87, 0xbfb8aa3b, v87
	v_mul_f32_e32 v88, 0xbfb8aa3b, v88
	v_exp_f32_e32 v1, v1
	v_exp_f32_e32 v86, v86
	v_exp_f32_e32 v87, v87
	v_exp_f32_e32 v88, v88
	v_add_f32_e32 v1, 1.0, v1
	v_add_f32_e32 v86, 1.0, v86
	v_add_f32_e32 v87, 1.0, v87
	v_add_f32_e32 v88, 1.0, v88
	v_add_u32_e32 v98, 0x60, v148
	v_lshlrev_b64 v[100:101], 11, v[114:115]
	v_rcp_f32_e32 v1, v1
	v_rcp_f32_e32 v86, v86
	v_rcp_f32_e32 v87, v87
	v_rcp_f32_e32 v88, v88
	v_ashrrev_i32_e32 v99, 31, v98
	v_lshl_add_u64 v[100:101], s[60:61], 0, v[100:101]
	v_lshlrev_b64 v[102:103], 10, v[98:99]
	v_lshl_add_u64 v[100:101], v[100:101], 0, v[146:147]
	v_lshl_add_u64 v[102:103], s[80:81], 0, v[102:103]
	global_store_dwordx4 v[100:101], v[90:93], off offset:1024
	v_lshl_add_u64 v[102:103], v[102:103], 0, v[146:147]
	s_waitcnt vmcnt(15)
	v_mov_b32_e32 v94, v188
	v_mov_b32_e32 v95, v189
	v_mov_b32_e32 v96, v190
	v_mov_b32_e32 v97, v191
	v_lshlrev_b32_e32 v89, 16, v94
	v_and_b32_e32 v90, 0xffff0000, v94
	v_lshlrev_b32_e32 v91, 16, v95
	v_and_b32_e32 v92, 0xffff0000, v95
	v_lshlrev_b32_e32 v93, 16, v96
	v_and_b32_e32 v94, 0xffff0000, v96
	v_lshlrev_b32_e32 v95, 16, v97
	v_and_b32_e32 v96, 0xffff0000, v97
	v_mul_f32_e32 v1, v1, v89
	v_mul_f32_e32 v89, v82, v93
	v_mul_f32_e32 v82, v86, v90
	v_mul_f32_e32 v86, v83, v94
	v_mul_f32_e32 v83, v87, v91
	v_mul_f32_e32 v87, v84, v95
	v_mul_f32_e32 v84, v88, v92
	v_mul_f32_e32 v85, v85, v96
	v_cvt_pk_bf16_f32 v82, v1, v82
	v_cvt_pk_bf16_f32 v83, v83, v84
	v_cvt_pk_bf16_f32 v84, v89, v86
	v_cvt_pk_bf16_f32 v85, v87, v85
	v_add_f32_e32 v1, v70, v78
	v_add_f32_e32 v70, v71, v79
	v_add_f32_e32 v71, v72, v80
	v_add_f32_e32 v72, v73, v81
	v_mul_f32_e32 v1, 0xbfb8aa3b, v1
	v_mul_f32_e32 v70, 0xbfb8aa3b, v70
	v_mul_f32_e32 v71, 0xbfb8aa3b, v71
	v_mul_f32_e32 v72, 0xbfb8aa3b, v72
	v_exp_f32_e32 v1, v1
	v_exp_f32_e32 v70, v70
	v_exp_f32_e32 v71, v71
	v_exp_f32_e32 v72, v72
	v_add_f32_e32 v1, 1.0, v1
	v_add_f32_e32 v70, 1.0, v70
	v_add_f32_e32 v71, 1.0, v71
	v_add_f32_e32 v72, 1.0, v72
	v_rcp_f32_e32 v1, v1
	v_rcp_f32_e32 v70, v70
	v_rcp_f32_e32 v71, v71
	v_rcp_f32_e32 v72, v72
	global_store_dwordx4 v[100:101], v[82:85], off offset:1280
	s_waitcnt vmcnt(15)
	v_mov_b32_e32 v86, v192
	v_mov_b32_e32 v87, v193
	v_mov_b32_e32 v88, v194
	v_mov_b32_e32 v89, v195
	v_lshlrev_b32_e32 v73, 16, v86
	v_and_b32_e32 v82, 0xffff0000, v86
	v_lshlrev_b32_e32 v83, 16, v87
	v_and_b32_e32 v84, 0xffff0000, v87
	v_lshlrev_b32_e32 v85, 16, v88
	v_and_b32_e32 v86, 0xffff0000, v88
	v_lshlrev_b32_e32 v87, 16, v89
	v_and_b32_e32 v88, 0xffff0000, v89
	v_mul_f32_e32 v1, v1, v73
	v_mul_f32_e32 v73, v66, v85
	v_mul_f32_e32 v66, v70, v82
	v_mul_f32_e32 v70, v67, v86
	v_mul_f32_e32 v67, v71, v83
	v_mul_f32_e32 v71, v68, v87
	v_mul_f32_e32 v68, v72, v84
	v_mul_f32_e32 v69, v69, v88
	v_cvt_pk_bf16_f32 v66, v1, v66
	v_cvt_pk_bf16_f32 v67, v67, v68
	v_cvt_pk_bf16_f32 v68, v73, v70
	v_cvt_pk_bf16_f32 v69, v71, v69
	v_add_f32_e32 v1, v54, v62
	v_add_f32_e32 v54, v55, v63
	v_add_f32_e32 v55, v56, v64
	v_add_f32_e32 v56, v57, v65
	v_mul_f32_e32 v1, 0xbfb8aa3b, v1
	v_mul_f32_e32 v54, 0xbfb8aa3b, v54
	v_mul_f32_e32 v55, 0xbfb8aa3b, v55
	v_mul_f32_e32 v56, 0xbfb8aa3b, v56
	v_exp_f32_e32 v1, v1
	v_exp_f32_e32 v54, v54
	v_exp_f32_e32 v55, v55
	v_exp_f32_e32 v56, v56
	v_add_f32_e32 v1, 1.0, v1
	v_add_f32_e32 v54, 1.0, v54
	v_add_f32_e32 v55, 1.0, v55
	v_add_f32_e32 v56, 1.0, v56
	v_add_u32_e32 v82, 0x70, v148
	v_lshlrev_b64 v[84:85], 11, v[98:99]
	v_rcp_f32_e32 v1, v1
	v_rcp_f32_e32 v54, v54
	v_rcp_f32_e32 v55, v55
	v_rcp_f32_e32 v56, v56
	v_ashrrev_i32_e32 v83, 31, v82
	v_lshl_add_u64 v[84:85], s[60:61], 0, v[84:85]
	v_lshlrev_b64 v[86:87], 10, v[82:83]
	v_lshl_add_u64 v[84:85], v[84:85], 0, v[146:147]
	v_lshl_add_u64 v[86:87], s[80:81], 0, v[86:87]
	global_store_dwordx4 v[84:85], v[66:69], off offset:1024
	v_lshl_add_u64 v[86:87], v[86:87], 0, v[146:147]
	s_waitcnt vmcnt(15)
	v_mov_b32_e32 v70, v196
	v_mov_b32_e32 v71, v197
	v_mov_b32_e32 v72, v198
	v_mov_b32_e32 v73, v199
	v_lshlrev_b32_e32 v57, 16, v70
	v_and_b32_e32 v66, 0xffff0000, v70
	v_lshlrev_b32_e32 v67, 16, v71
	v_and_b32_e32 v68, 0xffff0000, v71
	v_lshlrev_b32_e32 v69, 16, v72
	v_and_b32_e32 v70, 0xffff0000, v72
	v_lshlrev_b32_e32 v71, 16, v73
	v_and_b32_e32 v72, 0xffff0000, v73
	v_mul_f32_e32 v1, v1, v57
	v_mul_f32_e32 v57, v50, v69
	v_mul_f32_e32 v50, v54, v66
	v_mul_f32_e32 v54, v51, v70
	v_mul_f32_e32 v51, v55, v67
	v_mul_f32_e32 v55, v52, v71
	v_mul_f32_e32 v52, v56, v68
	v_mul_f32_e32 v53, v53, v72
	v_cvt_pk_bf16_f32 v50, v1, v50
	v_cvt_pk_bf16_f32 v51, v51, v52
	v_cvt_pk_bf16_f32 v52, v57, v54
	v_cvt_pk_bf16_f32 v53, v55, v53
	v_add_f32_e32 v1, v46, v78
	v_add_f32_e32 v46, v47, v79
	v_add_f32_e32 v47, v48, v80
	v_add_f32_e32 v48, v49, v81
	v_mul_f32_e32 v1, 0xbfb8aa3b, v1
	v_mul_f32_e32 v46, 0xbfb8aa3b, v46
	v_mul_f32_e32 v47, 0xbfb8aa3b, v47
	v_mul_f32_e32 v48, 0xbfb8aa3b, v48
	v_exp_f32_e32 v1, v1
	v_exp_f32_e32 v46, v46
	v_exp_f32_e32 v47, v47
	v_exp_f32_e32 v48, v48
	v_add_f32_e32 v1, 1.0, v1
	v_add_f32_e32 v46, 1.0, v46
	v_add_f32_e32 v47, 1.0, v47
	v_add_f32_e32 v48, 1.0, v48
	v_rcp_f32_e32 v1, v1
	v_rcp_f32_e32 v46, v46
	v_rcp_f32_e32 v47, v47
	v_rcp_f32_e32 v48, v48
	global_store_dwordx4 v[84:85], v[50:53], off offset:1280
	s_waitcnt vmcnt(15)
	v_mov_b32_e32 v54, v200
	v_mov_b32_e32 v55, v201
	v_mov_b32_e32 v56, v202
	v_mov_b32_e32 v57, v203
	v_lshlrev_b32_e32 v49, 16, v54
	v_and_b32_e32 v50, 0xffff0000, v54
	v_lshlrev_b32_e32 v51, 16, v55
	v_and_b32_e32 v52, 0xffff0000, v55
	v_lshlrev_b32_e32 v53, 16, v56
	v_and_b32_e32 v54, 0xffff0000, v56
	v_lshlrev_b32_e32 v55, 16, v57
	v_and_b32_e32 v56, 0xffff0000, v57
	v_mul_f32_e32 v1, v1, v49
	v_mul_f32_e32 v49, v42, v53
	v_mul_f32_e32 v42, v46, v50
	v_mul_f32_e32 v46, v43, v54
	v_mul_f32_e32 v43, v47, v51
	v_mul_f32_e32 v47, v44, v55
	v_mul_f32_e32 v44, v48, v52
	v_mul_f32_e32 v45, v45, v56
	v_cvt_pk_bf16_f32 v42, v1, v42
	v_cvt_pk_bf16_f32 v43, v43, v44
	v_cvt_pk_bf16_f32 v44, v49, v46
	v_cvt_pk_bf16_f32 v45, v47, v45
	v_add_f32_e32 v1, v38, v62
	v_add_f32_e32 v38, v39, v63
	v_add_f32_e32 v39, v40, v64
	v_add_f32_e32 v40, v41, v65
	v_mul_f32_e32 v1, 0xbfb8aa3b, v1
	v_mul_f32_e32 v38, 0xbfb8aa3b, v38
	v_mul_f32_e32 v39, 0xbfb8aa3b, v39
	v_mul_f32_e32 v40, 0xbfb8aa3b, v40
	v_exp_f32_e32 v1, v1
	v_exp_f32_e32 v38, v38
	v_exp_f32_e32 v39, v39
	v_exp_f32_e32 v40, v40
	v_add_f32_e32 v1, 1.0, v1
	v_add_f32_e32 v38, 1.0, v38
	v_add_f32_e32 v39, 1.0, v39
	v_add_f32_e32 v40, 1.0, v40
	v_add_u32_e32 v50, 0x80, v148
	v_lshlrev_b64 v[52:53], 11, v[82:83]
	v_rcp_f32_e32 v1, v1
	v_rcp_f32_e32 v38, v38
	v_rcp_f32_e32 v39, v39
	v_rcp_f32_e32 v40, v40
	v_ashrrev_i32_e32 v51, 31, v50
	v_lshl_add_u64 v[52:53], s[60:61], 0, v[52:53]
	v_lshlrev_b64 v[54:55], 10, v[50:51]
	v_lshl_add_u64 v[52:53], v[52:53], 0, v[146:147]
	v_lshl_add_u64 v[54:55], s[80:81], 0, v[54:55]
	global_store_dwordx4 v[52:53], v[42:45], off offset:1024
	v_lshl_add_u64 v[54:55], v[54:55], 0, v[146:147]
	s_waitcnt vmcnt(15)
	v_mov_b32_e32 v46, v204
	v_mov_b32_e32 v47, v205
	v_mov_b32_e32 v48, v206
	v_mov_b32_e32 v49, v207
	v_lshlrev_b32_e32 v41, 16, v46
	v_and_b32_e32 v42, 0xffff0000, v46
	v_lshlrev_b32_e32 v43, 16, v47
	v_and_b32_e32 v44, 0xffff0000, v47
	v_lshlrev_b32_e32 v45, 16, v48
	v_and_b32_e32 v46, 0xffff0000, v48
	v_lshlrev_b32_e32 v47, 16, v49
	v_and_b32_e32 v48, 0xffff0000, v49
	v_mul_f32_e32 v1, v1, v41
	v_mul_f32_e32 v41, v34, v45
	v_mul_f32_e32 v34, v38, v42
	v_mul_f32_e32 v38, v35, v46
	v_mul_f32_e32 v35, v39, v43
	v_mul_f32_e32 v39, v36, v47
	v_mul_f32_e32 v36, v40, v44
	v_mul_f32_e32 v37, v37, v48
	v_cvt_pk_bf16_f32 v34, v1, v34
	v_cvt_pk_bf16_f32 v35, v35, v36
	v_cvt_pk_bf16_f32 v36, v41, v38
	v_cvt_pk_bf16_f32 v37, v39, v37
	v_add_f32_e32 v1, v30, v78
	v_add_f32_e32 v30, v31, v79
	v_add_f32_e32 v31, v32, v80
	v_add_f32_e32 v32, v33, v81
	v_mul_f32_e32 v1, 0xbfb8aa3b, v1
	v_mul_f32_e32 v30, 0xbfb8aa3b, v30
	v_mul_f32_e32 v31, 0xbfb8aa3b, v31
	v_mul_f32_e32 v32, 0xbfb8aa3b, v32
	v_exp_f32_e32 v1, v1
	v_exp_f32_e32 v30, v30
	v_exp_f32_e32 v31, v31
	v_exp_f32_e32 v32, v32
	v_add_f32_e32 v1, 1.0, v1
	v_add_f32_e32 v30, 1.0, v30
	v_add_f32_e32 v31, 1.0, v31
	v_add_f32_e32 v32, 1.0, v32
	v_rcp_f32_e32 v1, v1
	v_rcp_f32_e32 v30, v30
	v_rcp_f32_e32 v31, v31
	v_rcp_f32_e32 v32, v32
	global_store_dwordx4 v[52:53], v[34:37], off offset:1280
	s_waitcnt vmcnt(15)
	v_mov_b32_e32 v38, v208
	v_mov_b32_e32 v39, v209
	v_mov_b32_e32 v40, v210
	v_mov_b32_e32 v41, v211
	v_lshlrev_b32_e32 v33, 16, v38
	v_and_b32_e32 v34, 0xffff0000, v38
	v_lshlrev_b32_e32 v35, 16, v39
	v_and_b32_e32 v36, 0xffff0000, v39
	v_lshlrev_b32_e32 v37, 16, v40
	v_and_b32_e32 v38, 0xffff0000, v40
	v_lshlrev_b32_e32 v39, 16, v41
	v_and_b32_e32 v40, 0xffff0000, v41
	v_mul_f32_e32 v1, v1, v33
	v_mul_f32_e32 v33, v26, v37
	v_mul_f32_e32 v26, v30, v34
	v_mul_f32_e32 v30, v27, v38
	v_mul_f32_e32 v27, v31, v35
	v_mul_f32_e32 v31, v28, v39
	v_mul_f32_e32 v28, v32, v36
	v_mul_f32_e32 v29, v29, v40
	v_cvt_pk_bf16_f32 v26, v1, v26
	v_cvt_pk_bf16_f32 v27, v27, v28
	v_cvt_pk_bf16_f32 v28, v33, v30
	v_cvt_pk_bf16_f32 v29, v31, v29
	v_add_f32_e32 v1, v22, v62
	v_add_f32_e32 v22, v23, v63
	v_add_f32_e32 v23, v24, v64
	v_add_f32_e32 v24, v25, v65
	v_mul_f32_e32 v1, 0xbfb8aa3b, v1
	v_mul_f32_e32 v22, 0xbfb8aa3b, v22
	v_mul_f32_e32 v23, 0xbfb8aa3b, v23
	v_mul_f32_e32 v24, 0xbfb8aa3b, v24
	v_exp_f32_e32 v1, v1
	v_exp_f32_e32 v22, v22
	v_exp_f32_e32 v23, v23
	v_exp_f32_e32 v24, v24
	v_add_f32_e32 v1, 1.0, v1
	v_add_f32_e32 v22, 1.0, v22
	v_add_f32_e32 v23, 1.0, v23
	v_add_f32_e32 v24, 1.0, v24
	v_add_u32_e32 v34, 0xffff15a0, v148
	v_lshlrev_b64 v[36:37], 11, v[50:51]
	v_rcp_f32_e32 v1, v1
	v_rcp_f32_e32 v22, v22
	v_rcp_f32_e32 v23, v23
	v_rcp_f32_e32 v24, v24
	v_ashrrev_i32_e32 v35, 31, v34
	v_lshl_add_u64 v[36:37], s[60:61], 0, v[36:37]
	v_lshlrev_b64 v[38:39], 10, v[34:35]
	v_lshl_add_u64 v[36:37], v[36:37], 0, v[146:147]
	v_lshl_add_u64 v[38:39], s[80:81], 0, v[38:39]
	global_store_dwordx4 v[36:37], v[26:29], off offset:1024
	v_lshl_add_u64 v[38:39], v[38:39], 0, v[146:147]
	s_waitcnt vmcnt(15)
	v_mov_b32_e32 v30, v216
	v_mov_b32_e32 v31, v217
	v_mov_b32_e32 v32, v218
	v_mov_b32_e32 v33, v219
	v_lshlrev_b32_e32 v25, 16, v30
	v_and_b32_e32 v26, 0xffff0000, v30
	v_lshlrev_b32_e32 v27, 16, v31
	v_and_b32_e32 v28, 0xffff0000, v31
	v_lshlrev_b32_e32 v29, 16, v32
	v_and_b32_e32 v30, 0xffff0000, v32
	v_lshlrev_b32_e32 v31, 16, v33
	v_and_b32_e32 v32, 0xffff0000, v33
	v_mul_f32_e32 v1, v1, v25
	v_mul_f32_e32 v25, v18, v29
	v_mul_f32_e32 v18, v22, v26
	v_mul_f32_e32 v22, v19, v30
	v_mul_f32_e32 v19, v23, v27
	v_mul_f32_e32 v23, v20, v31
	v_mul_f32_e32 v20, v24, v28
	v_mul_f32_e32 v21, v21, v32
	v_cvt_pk_bf16_f32 v18, v1, v18
	v_cvt_pk_bf16_f32 v19, v19, v20
	v_cvt_pk_bf16_f32 v20, v25, v22
	v_cvt_pk_bf16_f32 v21, v23, v21
	v_add_f32_e32 v1, v14, v78
	v_add_f32_e32 v14, v15, v79
	v_add_f32_e32 v15, v16, v80
	v_add_f32_e32 v16, v17, v81
	v_mul_f32_e32 v1, 0xbfb8aa3b, v1
	v_mul_f32_e32 v14, 0xbfb8aa3b, v14
	v_mul_f32_e32 v15, 0xbfb8aa3b, v15
	v_mul_f32_e32 v16, 0xbfb8aa3b, v16
	v_exp_f32_e32 v1, v1
	v_exp_f32_e32 v14, v14
	v_exp_f32_e32 v15, v15
	v_exp_f32_e32 v16, v16
	v_add_f32_e32 v1, 1.0, v1
	v_add_f32_e32 v14, 1.0, v14
	v_add_f32_e32 v15, 1.0, v15
	v_add_f32_e32 v16, 1.0, v16
	v_rcp_f32_e32 v1, v1
	v_rcp_f32_e32 v14, v14
	v_rcp_f32_e32 v15, v15
	v_rcp_f32_e32 v16, v16
	global_store_dwordx4 v[36:37], v[18:21], off offset:1280
	s_waitcnt vmcnt(15)
	v_mov_b32_e32 v22, v220
	v_mov_b32_e32 v23, v221
	v_mov_b32_e32 v24, v222
	v_mov_b32_e32 v25, v223
	v_lshlrev_b32_e32 v17, 16, v22
	v_and_b32_e32 v18, 0xffff0000, v22
	v_lshlrev_b32_e32 v19, 16, v23
	v_and_b32_e32 v20, 0xffff0000, v23
	v_lshlrev_b32_e32 v21, 16, v24
	v_and_b32_e32 v22, 0xffff0000, v24
	v_lshlrev_b32_e32 v23, 16, v25
	v_and_b32_e32 v24, 0xffff0000, v25
	v_mul_f32_e32 v1, v1, v17
	v_mul_f32_e32 v17, v10, v21
	v_mul_f32_e32 v10, v14, v18
	v_mul_f32_e32 v14, v11, v22
	v_mul_f32_e32 v11, v15, v19
	v_mul_f32_e32 v15, v12, v23
	v_mul_f32_e32 v12, v16, v20
	v_mul_f32_e32 v13, v13, v24
	v_cvt_pk_bf16_f32 v10, v1, v10
	v_cvt_pk_bf16_f32 v11, v11, v12
	v_cvt_pk_bf16_f32 v12, v17, v14
	v_cvt_pk_bf16_f32 v13, v15, v13
	v_add_f32_e32 v1, v6, v62
	v_add_f32_e32 v6, v7, v63
	v_add_f32_e32 v7, v8, v64
	v_add_f32_e32 v8, v9, v65
	v_mul_f32_e32 v1, 0xbfb8aa3b, v1
	v_mul_f32_e32 v6, 0xbfb8aa3b, v6
	v_mul_f32_e32 v7, 0xbfb8aa3b, v7
	v_mul_f32_e32 v8, 0xbfb8aa3b, v8
	v_exp_f32_e32 v1, v1
	v_exp_f32_e32 v6, v6
	v_exp_f32_e32 v7, v7
	v_exp_f32_e32 v8, v8
	v_add_f32_e32 v1, 1.0, v1
	v_add_f32_e32 v6, 1.0, v6
	v_add_f32_e32 v7, 1.0, v7
	v_add_f32_e32 v8, 1.0, v8
	v_lshlrev_b64 v[18:19], 11, v[34:35]
	v_rcp_f32_e32 v1, v1
	v_rcp_f32_e32 v6, v6
	v_rcp_f32_e32 v7, v7
	v_rcp_f32_e32 v8, v8
	v_lshl_add_u64 v[18:19], s[60:61], 0, v[18:19]
	v_lshl_add_u64 v[18:19], v[18:19], 0, v[146:147]
	global_store_dwordx4 v[18:19], v[10:13], off offset:1024
	s_waitcnt vmcnt(15)
	v_mov_b32_e32 v14, v224
	v_mov_b32_e32 v15, v225
	v_mov_b32_e32 v16, v226
	v_mov_b32_e32 v17, v227
	v_lshlrev_b32_e32 v9, 16, v14
	v_and_b32_e32 v10, 0xffff0000, v14
	v_lshlrev_b32_e32 v11, 16, v15
	v_and_b32_e32 v12, 0xffff0000, v15
	v_lshlrev_b32_e32 v13, 16, v16
	v_and_b32_e32 v14, 0xffff0000, v16
	v_lshlrev_b32_e32 v15, 16, v17
	v_and_b32_e32 v16, 0xffff0000, v17
	v_mul_f32_e32 v1, v1, v9
	v_mul_f32_e32 v9, v2, v13
	v_mul_f32_e32 v2, v6, v10
	v_mul_f32_e32 v6, v3, v14
	v_mul_f32_e32 v3, v7, v11
	v_mul_f32_e32 v7, v4, v15
	v_mul_f32_e32 v4, v8, v12
	v_mul_f32_e32 v5, v5, v16
	v_cvt_pk_bf16_f32 v2, v1, v2
	v_cvt_pk_bf16_f32 v3, v3, v4
	v_cvt_pk_bf16_f32 v4, v9, v6
	v_cvt_pk_bf16_f32 v5, v7, v5
	global_store_dwordx4 v[18:19], v[2:5], off offset:1280
	s_waitcnt vmcnt(0)
	s_barrier
